# v15 + w_out residual epilogue: residual loads 7 units deep in flight instead of 6 (one more free register slot)
# speedup vs baseline: 1.0022x; 1.0022x over previous
;     DI void operator()(const f32x4 (&acc)[2][2][4][2], const Unit& u, int wr, int wc, int fr, int fq) const {
;     ...
;         for (int bj = 0; bj < 2; ++bj) { const int col = col0 + bj * HALF; const f32x4 g0 = *(const f32x4*)(garow + col), g1 = *(const f32x4*)(garow + col + 4);
; #pragma unroll
;             for (int ai = 0; ai < 2; ++ai)
; #pragma unroll
;                 for (int m = 0; m < 4; ++m) { const size_t off = (size_t)(rin + ai * HALF + m * 16) * D + col;
;                     if (u.split) { float* sp = (float*)(P.ws + WS_SLAB) + ((size_t)u.sl * (NB * CTX) + (size_t)b * CTX) * D + off;
;                         *(f32x4*)sp = g0 * acc[ai][bj][m][0]; *(f32x4*)(sp + 4) = g1 * acc[ai][bj][m][1]; }
;                     else { const f32x4 x0 = *(const f32x4*)(rbase + off), x1 = *(const f32x4*)(rbase + off + 4);
;                         *(f32x4*)(dbase + off) = x0 + g0 * acc[ai][bj][m][0]; *(f32x4*)(dbase + off + 4) = x1 + g1 * acc[ai][bj][m][1]; } } }
.Lepi_wo_fast:
	v_mbcnt_lo_u32_b32 v204, -1, 0
	v_mbcnt_hi_u32_b32 v204, -1, v204
	v_readfirstlane_b32 s78, v182
	v_readfirstlane_b32 s79, v154
	v_readfirstlane_b32 s80, v178
	v_readfirstlane_b32 s81, v179
	v_readlane_b32 s82, v253, 14
	v_and_b32_e32 v211, 7, v204
	v_lshrrev_b32_e32 v205, 4, v204
	v_lshlrev_b32_e32 v205, 1, v205
	v_xor_b32_e32 v205, v205, v211
	v_lshlrev_b32_e32 v205, 4, v205
	v_lshl_or_b32 v205, v211, 7, v205
	v_bfe_u32 v206, v204, 3, 1
	v_lshl_or_b32 v205, v206, 13, v205
	v_lshrrev_b32_e32 v207, 3, v204
	v_xor_b32_e32 v209, v211, v207
	v_lshlrev_b32_e32 v209, 4, v209
	v_lshlrev_b32_e32 v210, 4, v211
	v_lshl_or_b32 v208, v207, 12, v210
	v_lshl_or_b32 v207, v207, 7, v209
	s_add_i32 s82, s82, 0xc000
	v_add_u32_e32 v205, s82, v205
	v_xor_b32_e32 v206, 16, v205
	v_add_u32_e32 v207, s82, v207
	v_add_u32_e32 v209, 0x8000, v208
	s_add_i32 s78, s78, s79
	s_lshl_b32 s78, s78, 2
	s_add_u32 s74, s18, s78
	s_addc_u32 s75, s19, 0
	s_add_u32 s76, s16, s78
	s_addc_u32 s77, s17, 0
	global_load_dwordx4 v[212:215], v210, s[80:81]
	global_load_dwordx4 v[216:219], v210, s[80:81] offset:512
	global_load_dwordx4 v[236:239], v208, s[74:75]
	global_load_dwordx4 v[240:243], v209, s[74:75]
	global_load_dwordx4 v[244:247], v208, s[74:75] offset:512
	global_load_dwordx4 v[192:195], v209, s[74:75] offset:512
	s_add_u32 s74, s74, 0x10000
	s_addc_u32 s75, s75, 0
	global_load_dwordx4 v[196:199], v208, s[74:75]
	global_load_dwordx4 v[186:189], v209, s[74:75]
	global_load_dwordx4 v[138:141], v208, s[74:75] offset:512
	ds_write_b128 v205, v[126:129]
	ds_write_b128 v206, v[122:125]
	ds_read_b128 v[220:223], v207
	ds_read_b128 v[224:227], v207 offset:8192
	ds_write_b128 v205, v[60:63]
	ds_write_b128 v206, v[56:59]
	ds_read_b128 v[228:231], v207
	ds_read_b128 v[232:235], v207 offset:8192
	s_waitcnt vmcnt(6) lgkmcnt(5)
	v_pk_fma_f32 v[220:221], v[220:221], v[212:213], v[236:237]
	v_pk_fma_f32 v[222:223], v[222:223], v[214:215], v[238:239]
	global_store_dwordx4 v208, v[220:223], s[76:77]
	global_load_dwordx4 v[236:239], v209, s[74:75] offset:512
	s_waitcnt vmcnt(7) lgkmcnt(4)
	v_pk_fma_f32 v[224:225], v[224:225], v[212:213], v[240:241]
	v_pk_fma_f32 v[226:227], v[226:227], v[214:215], v[242:243]
	global_store_dwordx4 v209, v[224:227], s[76:77]
	s_add_u32 s74, s74, 0x10000
	s_addc_u32 s75, s75, 0
	global_load_dwordx4 v[240:243], v208, s[74:75]
	ds_write_b128 v205, v[118:121]
	ds_write_b128 v206, v[114:117]
	ds_read_b128 v[220:223], v207
	ds_read_b128 v[224:227], v207 offset:8192
	s_waitcnt vmcnt(8) lgkmcnt(5)
	v_pk_fma_f32 v[228:229], v[228:229], v[216:217], v[244:245]
	v_pk_fma_f32 v[230:231], v[230:231], v[218:219], v[246:247]
	global_store_dwordx4 v208, v[228:231], s[76:77] offset:512
	global_load_dwordx4 v[244:247], v209, s[74:75]
	s_waitcnt vmcnt(9) lgkmcnt(4)
	v_pk_fma_f32 v[232:233], v[232:233], v[216:217], v[192:193]
	v_pk_fma_f32 v[234:235], v[234:235], v[218:219], v[194:195]
	global_store_dwordx4 v209, v[232:235], s[76:77] offset:512
	global_load_dwordx4 v[192:195], v208, s[74:75] offset:512
	ds_write_b128 v205, v[52:55]
	ds_write_b128 v206, v[48:51]
	ds_read_b128 v[228:231], v207
	ds_read_b128 v[232:235], v207 offset:8192
	s_waitcnt vmcnt(10) lgkmcnt(5)
	v_pk_fma_f32 v[220:221], v[220:221], v[212:213], v[196:197]
	v_pk_fma_f32 v[222:223], v[222:223], v[214:215], v[198:199]
	s_add_u32 s76, s76, 0x10000
	s_addc_u32 s77, s77, 0
	global_store_dwordx4 v208, v[220:223], s[76:77]
	global_load_dwordx4 v[196:199], v209, s[74:75] offset:512
	s_waitcnt vmcnt(11) lgkmcnt(4)
	v_pk_fma_f32 v[224:225], v[224:225], v[212:213], v[186:187]
	v_pk_fma_f32 v[226:227], v[226:227], v[214:215], v[188:189]
	global_store_dwordx4 v209, v[224:227], s[76:77]
	s_add_u32 s74, s74, 0x10000
	s_addc_u32 s75, s75, 0
	global_load_dwordx4 v[186:189], v208, s[74:75]
	ds_write_b128 v205, v[108:111]
	ds_write_b128 v206, v[104:107]
	ds_read_b128 v[220:223], v207
	ds_read_b128 v[224:227], v207 offset:8192
	s_waitcnt vmcnt(12) lgkmcnt(5)
	v_pk_fma_f32 v[228:229], v[228:229], v[216:217], v[138:139]
	v_pk_fma_f32 v[230:231], v[230:231], v[218:219], v[140:141]
	global_store_dwordx4 v208, v[228:231], s[76:77] offset:512
	global_load_dwordx4 v[138:141], v209, s[74:75]
	s_waitcnt vmcnt(12) lgkmcnt(4)
	v_pk_fma_f32 v[232:233], v[232:233], v[216:217], v[236:237]
	v_pk_fma_f32 v[234:235], v[234:235], v[218:219], v[238:239]
	global_store_dwordx4 v209, v[232:235], s[76:77] offset:512
	global_load_dwordx4 v[236:239], v208, s[74:75] offset:512
	ds_write_b128 v205, v[44:47]
	ds_write_b128 v206, v[40:43]
	ds_read_b128 v[228:231], v207
	ds_read_b128 v[232:235], v207 offset:8192
	s_waitcnt vmcnt(12) lgkmcnt(5)
	v_pk_fma_f32 v[220:221], v[220:221], v[212:213], v[240:241]
	v_pk_fma_f32 v[222:223], v[222:223], v[214:215], v[242:243]
	s_add_u32 s76, s76, 0x10000
	s_addc_u32 s77, s77, 0
	global_store_dwordx4 v208, v[220:223], s[76:77]
	global_load_dwordx4 v[240:243], v209, s[74:75] offset:512
	s_waitcnt vmcnt(12) lgkmcnt(4)
	v_pk_fma_f32 v[224:225], v[224:225], v[212:213], v[244:245]
	v_pk_fma_f32 v[226:227], v[226:227], v[214:215], v[246:247]
	global_store_dwordx4 v209, v[224:227], s[76:77]
	s_add_u32 s74, s74, 0x50000
	s_addc_u32 s75, s75, 0
	global_load_dwordx4 v[244:247], v208, s[74:75]
	ds_write_b128 v205, v[100:103]
	ds_write_b128 v206, v[96:99]
	ds_read_b128 v[220:223], v207
	ds_read_b128 v[224:227], v207 offset:8192
	s_waitcnt vmcnt(12) lgkmcnt(5)
	v_pk_fma_f32 v[228:229], v[228:229], v[216:217], v[192:193]
	v_pk_fma_f32 v[230:231], v[230:231], v[218:219], v[194:195]
	global_store_dwordx4 v208, v[228:231], s[76:77] offset:512
	global_load_dwordx4 v[192:195], v209, s[74:75]
	s_waitcnt vmcnt(12) lgkmcnt(4)
;     DI void operator()(const f32x4 (&acc)[2][2][4][2], const Unit& u, int wr, int wc, int fr, int fq) const {
;     ...
;         for (int bj = 0; bj < 2; ++bj) { const int col = col0 + bj * HALF; const f32x4 g0 = *(const f32x4*)(garow + col), g1 = *(const f32x4*)(garow + col + 4);
; #pragma unroll
;             for (int ai = 0; ai < 2; ++ai)
; #pragma unroll
;                 for (int m = 0; m < 4; ++m) { const size_t off = (size_t)(rin + ai * HALF + m * 16) * D + col;
;                     if (u.split) { float* sp = (float*)(P.ws + WS_SLAB) + ((size_t)u.sl * (NB * CTX) + (size_t)b * CTX) * D + off;
;                         *(f32x4*)sp = g0 * acc[ai][bj][m][0]; *(f32x4*)(sp + 4) = g1 * acc[ai][bj][m][1]; }
;                     else { const f32x4 x0 = *(const f32x4*)(rbase + off), x1 = *(const f32x4*)(rbase + off + 4);
;                         *(f32x4*)(dbase + off) = x0 + g0 * acc[ai][bj][m][0]; *(f32x4*)(dbase + off + 4) = x1 + g1 * acc[ai][bj][m][1]; } } }
	v_pk_fma_f32 v[232:233], v[232:233], v[216:217], v[196:197]
	v_pk_fma_f32 v[234:235], v[234:235], v[218:219], v[198:199]
	global_store_dwordx4 v209, v[232:235], s[76:77] offset:512
	global_load_dwordx4 v[196:199], v208, s[74:75] offset:512
	ds_write_b128 v205, v[36:39]
	ds_write_b128 v206, v[32:35]
	ds_read_b128 v[228:231], v207
	ds_read_b128 v[232:235], v207 offset:8192
	s_waitcnt vmcnt(12) lgkmcnt(5)
	v_pk_fma_f32 v[220:221], v[220:221], v[212:213], v[186:187]
	v_pk_fma_f32 v[222:223], v[222:223], v[214:215], v[188:189]
	s_add_u32 s76, s76, 0x10000
	s_addc_u32 s77, s77, 0
	global_store_dwordx4 v208, v[220:223], s[76:77]
	global_load_dwordx4 v[186:189], v209, s[74:75] offset:512
	s_waitcnt vmcnt(12) lgkmcnt(4)
	v_pk_fma_f32 v[224:225], v[224:225], v[212:213], v[138:139]
	v_pk_fma_f32 v[226:227], v[226:227], v[214:215], v[140:141]
	global_store_dwordx4 v209, v[224:227], s[76:77]
	s_add_u32 s74, s74, 0x10000
	s_addc_u32 s75, s75, 0
	global_load_dwordx4 v[138:141], v208, s[74:75]
	ds_write_b128 v205, v[92:95]
	ds_write_b128 v206, v[88:91]
	ds_read_b128 v[220:223], v207
	ds_read_b128 v[224:227], v207 offset:8192
	s_waitcnt vmcnt(12) lgkmcnt(5)
	v_pk_fma_f32 v[228:229], v[228:229], v[216:217], v[236:237]
	v_pk_fma_f32 v[230:231], v[230:231], v[218:219], v[238:239]
	global_store_dwordx4 v208, v[228:231], s[76:77] offset:512
	global_load_dwordx4 v[236:239], v209, s[74:75]
	s_waitcnt vmcnt(12) lgkmcnt(4)
	v_pk_fma_f32 v[232:233], v[232:233], v[216:217], v[240:241]
	v_pk_fma_f32 v[234:235], v[234:235], v[218:219], v[242:243]
	global_store_dwordx4 v209, v[232:235], s[76:77] offset:512
	global_load_dwordx4 v[240:243], v208, s[74:75] offset:512
	ds_write_b128 v205, v[28:31]
	ds_write_b128 v206, v[24:27]
	ds_read_b128 v[228:231], v207
	ds_read_b128 v[232:235], v207 offset:8192
	s_waitcnt vmcnt(12) lgkmcnt(5)
	v_pk_fma_f32 v[220:221], v[220:221], v[212:213], v[244:245]
	v_pk_fma_f32 v[222:223], v[222:223], v[214:215], v[246:247]
	s_add_u32 s76, s76, 0x50000
	s_addc_u32 s77, s77, 0
	global_store_dwordx4 v208, v[220:223], s[76:77]
	global_load_dwordx4 v[244:247], v209, s[74:75] offset:512
	s_waitcnt vmcnt(12) lgkmcnt(4)
	v_pk_fma_f32 v[224:225], v[224:225], v[212:213], v[192:193]
	v_pk_fma_f32 v[226:227], v[226:227], v[214:215], v[194:195]
	global_store_dwordx4 v209, v[224:227], s[76:77]
	s_add_u32 s74, s74, 0x10000
	s_addc_u32 s75, s75, 0
	global_load_dwordx4 v[192:195], v208, s[74:75]
	ds_write_b128 v205, v[84:87]
	ds_write_b128 v206, v[80:83]
	ds_read_b128 v[220:223], v207
	ds_read_b128 v[224:227], v207 offset:8192
	s_waitcnt vmcnt(12) lgkmcnt(5)
	v_pk_fma_f32 v[228:229], v[228:229], v[216:217], v[196:197]
	v_pk_fma_f32 v[230:231], v[230:231], v[218:219], v[198:199]
	global_store_dwordx4 v208, v[228:231], s[76:77] offset:512
	global_load_dwordx4 v[196:199], v209, s[74:75]
	s_waitcnt vmcnt(12) lgkmcnt(4)
	v_pk_fma_f32 v[232:233], v[232:233], v[216:217], v[186:187]
	v_pk_fma_f32 v[234:235], v[234:235], v[218:219], v[188:189]
	global_store_dwordx4 v209, v[232:235], s[76:77] offset:512
	global_load_dwordx4 v[186:189], v208, s[74:75] offset:512
	ds_write_b128 v205, v[20:23]
	ds_write_b128 v206, v[16:19]
	ds_read_b128 v[228:231], v207
	ds_read_b128 v[232:235], v207 offset:8192
	s_waitcnt vmcnt(12) lgkmcnt(5)
	v_pk_fma_f32 v[220:221], v[220:221], v[212:213], v[138:139]
	v_pk_fma_f32 v[222:223], v[222:223], v[214:215], v[140:141]
	s_add_u32 s76, s76, 0x10000
	s_addc_u32 s77, s77, 0
	global_store_dwordx4 v208, v[220:223], s[76:77]
	global_load_dwordx4 v[138:141], v209, s[74:75] offset:512
	s_waitcnt vmcnt(12) lgkmcnt(4)
	v_pk_fma_f32 v[224:225], v[224:225], v[212:213], v[236:237]
	v_pk_fma_f32 v[226:227], v[226:227], v[214:215], v[238:239]
	global_store_dwordx4 v209, v[224:227], s[76:77]
	s_add_u32 s74, s74, 0x10000
	s_addc_u32 s75, s75, 0
	global_load_dwordx4 v[236:239], v208, s[74:75]
	ds_write_b128 v205, v[76:79]
	ds_write_b128 v206, v[72:75]
	ds_read_b128 v[220:223], v207
	ds_read_b128 v[224:227], v207 offset:8192
	s_waitcnt vmcnt(12) lgkmcnt(5)
	v_pk_fma_f32 v[228:229], v[228:229], v[216:217], v[240:241]
	v_pk_fma_f32 v[230:231], v[230:231], v[218:219], v[242:243]
	global_store_dwordx4 v208, v[228:231], s[76:77] offset:512
	global_load_dwordx4 v[240:243], v209, s[74:75]
	s_waitcnt vmcnt(12) lgkmcnt(4)
	v_pk_fma_f32 v[232:233], v[232:233], v[216:217], v[244:245]
	v_pk_fma_f32 v[234:235], v[234:235], v[218:219], v[246:247]
	global_store_dwordx4 v209, v[232:235], s[76:77] offset:512
	global_load_dwordx4 v[244:247], v208, s[74:75] offset:512
	ds_write_b128 v205, v[12:15]
	ds_write_b128 v206, v[8:11]
	ds_read_b128 v[228:231], v207
	ds_read_b128 v[232:235], v207 offset:8192
	s_waitcnt vmcnt(12) lgkmcnt(5)
	v_pk_fma_f32 v[220:221], v[220:221], v[212:213], v[192:193]
	v_pk_fma_f32 v[222:223], v[222:223], v[214:215], v[194:195]
	s_add_u32 s76, s76, 0x10000
	s_addc_u32 s77, s77, 0
	global_store_dwordx4 v208, v[220:223], s[76:77]
	global_load_dwordx4 v[192:195], v209, s[74:75] offset:512
	s_waitcnt vmcnt(12) lgkmcnt(4)
	v_pk_fma_f32 v[224:225], v[224:225], v[212:213], v[196:197]
	v_pk_fma_f32 v[226:227], v[226:227], v[214:215], v[198:199]
	global_store_dwordx4 v209, v[224:227], s[76:77]
	ds_write_b128 v205, v[68:71]
	ds_write_b128 v206, v[64:67]
	ds_read_b128 v[220:223], v207
	ds_read_b128 v[224:227], v207 offset:8192
	s_waitcnt vmcnt(11) lgkmcnt(5)
	v_pk_fma_f32 v[228:229], v[228:229], v[216:217], v[186:187]
	v_pk_fma_f32 v[230:231], v[230:231], v[218:219], v[188:189]
	global_store_dwordx4 v208, v[228:231], s[76:77] offset:512
	s_waitcnt vmcnt(10) lgkmcnt(4)
	v_pk_fma_f32 v[232:233], v[232:233], v[216:217], v[138:139]
	v_pk_fma_f32 v[234:235], v[234:235], v[218:219], v[140:141]
	global_store_dwordx4 v209, v[232:235], s[76:77] offset:512
	ds_write_b128 v205, v[4:7]
	ds_write_b128 v206, v[0:3]
	ds_read_b128 v[228:231], v207
	ds_read_b128 v[232:235], v207 offset:8192
	s_waitcnt vmcnt(9) lgkmcnt(5)
	v_pk_fma_f32 v[220:221], v[220:221], v[212:213], v[236:237]
	v_pk_fma_f32 v[222:223], v[222:223], v[214:215], v[238:239]
	s_add_u32 s76, s76, 0x10000
	s_addc_u32 s77, s77, 0
	global_store_dwordx4 v208, v[220:223], s[76:77]
	s_waitcnt vmcnt(8) lgkmcnt(4)
	v_pk_fma_f32 v[224:225], v[224:225], v[212:213], v[240:241]
	v_pk_fma_f32 v[226:227], v[226:227], v[214:215], v[242:243]
	global_store_dwordx4 v209, v[224:227], s[76:77]
	s_waitcnt vmcnt(7) lgkmcnt(1)
	v_pk_fma_f32 v[228:229], v[228:229], v[216:217], v[244:245]
	v_pk_fma_f32 v[230:231], v[230:231], v[218:219], v[246:247]
	global_store_dwordx4 v208, v[228:231], s[76:77] offset:512
	s_waitcnt vmcnt(6) lgkmcnt(0)
	v_pk_fma_f32 v[232:233], v[232:233], v[216:217], v[192:193]
	v_pk_fma_f32 v[234:235], v[234:235], v[218:219], v[194:195]
	global_store_dwordx4 v209, v[232:235], s[76:77] offset:512
	s_andn2_b64 vcc, exec, s[8:9]
	s_mov_b64 s[0:1], -1
	s_cbranch_vccnz .LBB0_686
	s_branch .Lepi_wo_after
